# P4 item epilogue: 4x4 lane-row transpose + dwordx4 stores; next item's Q_lat prefetched at last chunk
# speedup vs baseline: 1.0304x; 1.0304x over previous
; #define LAS __attribute__((address_space(3)))
; __device__ __forceinline__ unsigned cvt_pk_bf16(float lo, float hi) { unsigned r; asm("v_cvt_pk_bf16_f32 %0, %1, %2" : "=v"(r) : "v"(lo), "v"(hi)); return r; }
; __device__ __forceinline__ void p4_attn(const Params& p, unsigned char* lds, int bid, int nb, bool dry) {
;     ...
;   for (int round = 0; round * nb < T / 4; ++round) {
;     const int item = round * nb + (bid + round * 37) % nb;
;     const int tg0 = item * 4, b = tg0 >> 11, t0 = tg0 & 2047, t = t0 + tok, tg = tg0 + tok;
;     const int nk = min(t + 1, 256), nkmax = min(t0 + 4, 256), nch = (nkmax + 31) >> 5;
;     ((LAS unsigned*)idxs)[tid] = ((const unsigned*)(idxg + (size_t)tg0 * 256))[tid];
;     unsigned char* qrow = QL + (size_t)tg * 8192 + head * 256;
;     bf16x8 qB[8];
; #pragma unroll
;     for (int s = 0; s < 8; ++s) { const u32x2 qw = *(const u32x2*)(qrow + 32 * s + 8 * g);
;       typedef float f32x2v __attribute__((ext_vector_type(2)));
;       const f32x2v a0 = __builtin_amdgcn_cvt_pk_f32_fp8(qw[0], false), a1 = __builtin_amdgcn_cvt_pk_f32_fp8(qw[0], true), a2 = __builtin_amdgcn_cvt_pk_f32_fp8(qw[1], false), a3 = __builtin_amdgcn_cvt_pk_f32_fp8(qw[1], true);
;       u32x4 pw; pw[0] = cvt_pk_bf16(a0[0], a0[1]); pw[1] = cvt_pk_bf16(a1[0], a1[1]); pw[2] = cvt_pk_bf16(a2[0], a2[1]); pw[3] = cvt_pk_bf16(a3[0], a3[1]);
;       union { u32x4 u; bf16x8 v; } cv; cv.u = pw; qB[s] = cv.v; }
;     epoch += 2u; pair_sync(pcnt, epoch, lane);
.LBB0_988:
	s_or_b64 exec, exec, s[4:5]
	v_cmp_gt_i32_e32 vcc, 4, v2
	s_and_saveexec_b64 s[4:5], vcc
	v_add_u32_e32 v0, 0x26880, v0
	v_mov_b32_e32 v1, 0
	ds_write_b32 v0, v1
	s_or_b64 exec, exec, s[4:5]
	v_bfe_u32 v5, v2, 4, 2
	v_bfe_u32 v0, v2, 3, 1
	v_mov_b32_e32 v0, v5
	v_lshlrev_b32_e32 v162, 4, v0
	v_bfe_u32 v0, v2, 2, 2
	v_lshlrev_b32_e32 v148, 2, v5
	v_or_b32_e32 v0, v148, v0
	s_ashr_i32 s0, s3, 7
	s_lshr_b32 s3, s3, 2
	v_mul_u32_u24_e32 v163, 0x220, v0
	v_lshrrev_b32_e32 v0, 1, v2
	v_bfe_u32 v8, v2, 5, 1
	v_and_b32_e32 v6, 15, v2
	s_and_b32 s3, s3, 16
	v_and_b32_e32 v0, 1, v0
	v_readlane_b32 s4, v254, 36
	v_or_b32_e32 v7, s3, v6
	v_lshlrev_b32_e32 v164, 4, v0
	v_lshlrev_b32_e32 v0, 3, v2
	v_ashrrev_i32_e32 v3, 31, v2
	v_readlane_b32 s5, v254, 37
	v_and_b32_e32 v165, 8, v0
	v_and_b32_e32 v10, 31, v2
	v_lshl_add_u64 v[150:151], v[2:3], 2, s[4:5]
	v_lshlrev_b32_e32 v0, 8, v7
	v_mov_b32_e32 v1, 0
	v_readlane_b32 s4, v254, 42
	v_lshl_add_u64 v[152:153], s[92:93], 0, v[0:1]
	v_lshlrev_b32_e32 v0, 4, v10
	v_readlane_b32 s5, v254, 43
	v_lshl_or_b32 v9, v8, 3, s3
	s_add_i32 s3, 0, 0x26080
	v_lshl_add_u64 v[156:157], s[4:5], 0, v[0:1]
	s_lshl_b32 s4, s0, 9
	s_lshl_b32 s2, s0, 2
	v_lshl_add_u32 v166, v2, 2, s3
	s_add_i32 s3, s3, s4
	s_mul_i32 s4, s0, 0x4400
	v_and_b32_e32 v0, 31, v2
	s_add_i32 s2, s2, 0
	v_and_b32_e32 v4, 63, v2
	s_add_i32 s5, s4, 0
	v_lshlrev_b32_e32 v0, 4, v0
	s_add_i32 s4, 0, 0x22000
	v_mul_u32_u24_e32 v2, 0x220, v9
	s_mov_b32 s1, 0
	s_add_i32 s2, s2, 0x26880
	v_lshlrev_b32_e32 v154, 3, v5
	v_mov_b32_e32 v155, v1
	v_cmp_eq_u32_e64 s[8:9], 0, v4
	v_lshl_add_u32 v167, v9, 1, s3
	v_mul_u32_u24_e32 v168, 0x220, v6
	v_lshl_add_u32 v169, v7, 2, s4
	v_mov_b32_e32 v149, v1
	v_add3_u32 v170, s5, v0, v2
	s_movk_i32 s16, 0x80
	s_mov_b32 s4, 0x3e0293ee
	s_mov_b32 s17, 0xf149f2ca
	s_mov_b32 s18, 0x41800000
	v_mov_b32_e32 v171, 9
	v_mov_b32_e32 v172, 0x80
	v_mov_b32_e32 v173, 0xf149f2ca
	s_mov_b32 s10, 0
	s_mov_b32 s19, 0
	s_mov_b32 s20, 0
	s_lshl_b32 s28, s88, 11
	s_mov_b32 s29, 0
	v_lshl_add_u64 v[2:3], v[150:151], 0, s[28:29]
	global_load_dword v255, v[2:3], off
	s_lshl_b32 s28, s88, 2
	s_add_i32 s28, s28, s0
	s_lshl_b32 s28, s28, 13
	v_lshl_add_u64 v[194:195], v[152:153], 0, s[28:29]
	v_lshl_add_u64 v[194:195], v[194:195], 0, v[154:155]
	global_load_dwordx2 v[218:219], v[194:195], off
	global_load_dwordx2 v[220:221], v[194:195], off offset:32
	global_load_dwordx2 v[222:223], v[194:195], off offset:64
	global_load_dwordx2 v[224:225], v[194:195], off offset:96
	global_load_dwordx2 v[226:227], v[194:195], off offset:128
	global_load_dwordx2 v[228:229], v[194:195], off offset:160
	global_load_dwordx2 v[230:231], v[194:195], off offset:192
	global_load_dwordx2 v[232:233], v[194:195], off offset:224
	s_waitcnt vmcnt(0)
	s_waitcnt lgkmcnt(0)
	s_barrier
.LBB0_991:
	s_mul_i32 s11, s20, 37
	s_add_i32 s11, s11, s88
	s_ashr_i32 s12, s11, 31
	s_abs_i32 s11, s11
	v_readlane_b32 s13, v254, 32
	s_mul_hi_u32 s13, s11, s13
	v_readlane_b32 s14, v254, 33
	s_mul_i32 s13, s13, s14
	s_sub_i32 s11, s11, s13
	s_sub_i32 s13, s11, s14
	s_cmp_ge_u32 s11, s14
	s_cselect_b32 s11, s13, s11
	s_sub_i32 s13, s11, s14
	s_cmp_ge_u32 s11, s14
	s_cselect_b32 s11, s13, s11
	s_xor_b32 s11, s11, s12
	s_sub_i32 s22, s11, s12
	s_add_i32 s21, s22, s10
	s_lshl_b32 s10, s21, 2
	s_add_i32 s12, s10, s0
	s_ashr_i32 s11, s10, 31
	s_ashr_i32 s13, s12, 31
	s_lshl_b64 s[14:15], s[10:11], 9
	s_lshl_b64 s[12:13], s[12:13], 13
	v_lshl_add_u64 v[158:159], v[152:153], 0, s[12:13]
	s_waitcnt vmcnt(12)
	ds_write_b32 v166, v255
	s_and_saveexec_b64 s[12:13], s[8:9]
	s_cbranch_execz .LBB0_994
	s_mov_b64 s[14:15], exec
	v_mbcnt_lo_u32_b32 v0, s14, 0
	v_mbcnt_hi_u32_b32 v0, s15, v0
	v_cmp_eq_u32_e32 vcc, 0, v0
	s_and_b64 s[24:25], exec, vcc
	s_mov_b64 exec, s[24:25]
	s_bcnt1_i32_b64 s11, s[14:15]
	v_mov_b32_e32 v0, s2
	v_mov_b32_e32 v2, s11
	ds_add_u32 v0, v2

; #define LAS __attribute__((address_space(3)))
; __device__ __forceinline__ unsigned cvt_pk_bf16(float lo, float hi) { unsigned r; asm("v_cvt_pk_bf16_f32 %0, %1, %2" : "=v"(r) : "v"(lo), "v"(hi)); return r; }
; #define P4_LOAD(ch) do { const u32x4 kk_ = *(const LAS u32x4*)(idxs + tok * 256 + (ch) * 32 + wrow); \
;       _Pragma("unroll") for (int i = 0; i < 8; ++i) { \
;       const int key = (int)((kk_[i >> 1] >> (16 * (i & 1))) & 0xffffu); stg[i] = *(const u32x4*)(cbase + (size_t)key * 256); } } while (0)
; #define P4_WRITE(bufp) do { _Pragma("unroll") for (int i = 0; i < 8; ++i) \
;       *(LAS u32x4*)((bufp) + (wrow + i) * CROW + 16 * (wch ^ (lane >> 5))) = stg[i]; } while (0)
; __device__ __forceinline__ void p4_attn(const Params& p, unsigned char* lds, int bid, int nb, bool dry) {
;     ...
;     const int item = round * nb + (bid + round * 37) % nb;
;     const int tg0 = item * 4, b = tg0 >> 11, t0 = tg0 & 2047, t = t0 + tok, tg = tg0 + tok;
;     const int nk = min(t + 1, 256), nkmax = min(t0 + 4, 256), nch = (nkmax + 31) >> 5;
;     ((LAS unsigned*)idxs)[tid] = ((const unsigned*)(idxg + (size_t)tg0 * 256))[tid];
;     unsigned char* qrow = QL + (size_t)tg * 8192 + head * 256;
;     bf16x8 qB[8];
; #pragma unroll
;     for (int s = 0; s < 8; ++s) { const u32x2 qw = *(const u32x2*)(qrow + 32 * s + 8 * g);
;       typedef float f32x2v __attribute__((ext_vector_type(2)));
;       const f32x2v a0 = __builtin_amdgcn_cvt_pk_f32_fp8(qw[0], false), a1 = __builtin_amdgcn_cvt_pk_f32_fp8(qw[0], true), a2 = __builtin_amdgcn_cvt_pk_f32_fp8(qw[1], false), a3 = __builtin_amdgcn_cvt_pk_f32_fp8(qw[1], true);
;       u32x4 pw; pw[0] = cvt_pk_bf16(a0[0], a0[1]); pw[1] = cvt_pk_bf16(a1[0], a1[1]); pw[2] = cvt_pk_bf16(a2[0], a2[1]); pw[3] = cvt_pk_bf16(a3[0], a3[1]);
;       union { u32x4 u; bf16x8 v; } cv; cv.u = pw; qB[s] = cv.v; }
;     epoch += 2u; pair_sync(pcnt, epoch, lane);
;     u32x4 stg[8];
;     const bf16_t* cbase = ckvn + (size_t)b * L * 256 + wch * 8;
;     ...
;     P4_LOAD(0);
;     P4_WRITE(cbuf + tok * CTOK);
.LBB0_996:
	ds_read_b128 v[36:39], v167
	s_ashr_i32 s12, s21, 9
	s_ashr_i32 s13, s12, 31
	s_lshl_b64 s[12:13], s[12:13], 20
	v_lshl_add_u64 v[160:161], v[156:157], 0, s[12:13]
	s_waitcnt lgkmcnt(0)
	v_lshlrev_b32_e32 v0, 9, v36
	v_and_b32_e32 v0, 0x1fffe00, v0
	v_lshl_add_u64 v[2:3], v[160:161], 0, v[0:1]
	v_lshlrev_b32_sdwa v0, v171, v36 dst_sel:DWORD dst_unused:UNUSED_PAD src0_sel:DWORD src1_sel:WORD_1
	v_lshl_add_u64 v[40:41], v[160:161], 0, v[0:1]
	v_lshlrev_b32_e32 v0, 9, v37
	v_and_b32_e32 v0, 0x1fffe00, v0
	global_load_dwordx4 v[44:47], v[2:3], off
	global_load_dwordx4 v[48:51], v[40:41], off
	v_lshl_add_u64 v[2:3], v[160:161], 0, v[0:1]
	v_lshlrev_b32_sdwa v0, v171, v37 dst_sel:DWORD dst_unused:UNUSED_PAD src0_sel:DWORD src1_sel:WORD_1
	v_lshl_add_u64 v[36:37], v[160:161], 0, v[0:1]
	v_lshlrev_b32_e32 v0, 9, v38
	v_and_b32_e32 v0, 0x1fffe00, v0
	global_load_dwordx4 v[60:63], v[2:3], off
	global_load_dwordx4 v[68:71], v[36:37], off
	v_lshl_add_u64 v[2:3], v[160:161], 0, v[0:1]
	v_lshlrev_b32_sdwa v0, v171, v38 dst_sel:DWORD dst_unused:UNUSED_PAD src0_sel:DWORD src1_sel:WORD_1
	v_lshl_add_u64 v[36:37], v[160:161], 0, v[0:1]
	v_lshlrev_b32_e32 v0, 9, v39
	v_and_b32_e32 v0, 0x1fffe00, v0
	global_load_dwordx4 v[84:87], v[2:3], off
	global_load_dwordx4 v[88:91], v[36:37], off
	v_lshl_add_u64 v[2:3], v[160:161], 0, v[0:1]
	v_lshlrev_b32_sdwa v0, v171, v39 dst_sel:DWORD dst_unused:UNUSED_PAD src0_sel:DWORD src1_sel:WORD_1
	global_load_dwordx4 v[100:103], v[2:3], off
	v_lshl_add_u64 v[2:3], v[160:161], 0, v[0:1]
	global_load_dwordx4 v[108:111], v[2:3], off
	s_add_i32 s28, s20, 1
	s_mul_i32 s29, s28, s89
	s_mul_i32 s30, s28, 37
	s_add_i32 s30, s30, s88
	v_readlane_b32 s31, v254, 32
	s_mul_hi_u32 s31, s30, s31
	v_readlane_b32 s33, v254, 33
	s_mul_i32 s31, s31, s33
	s_sub_i32 s30, s30, s31
	s_sub_i32 s31, s30, s33
	s_cmp_ge_u32 s30, s33
	s_cselect_b32 s30, s31, s30
	s_sub_i32 s31, s30, s33
	s_cmp_ge_u32 s30, s33
	s_cselect_b32 s30, s31, s30
	s_add_i32 s30, s30, s29
	s_cmpk_gt_i32 s29, 0x1fff
	s_cselect_b32 s30, s21, s30
	s_mov_b32 s36, s30
	s_lshl_b32 s30, s30, 11
	s_mov_b32 s31, 0
	v_lshl_add_u64 v[2:3], v[150:151], 0, s[30:31]
	global_load_dword v255, v[2:3], off
	s_waitcnt vmcnt(20)
	v_cvt_pk_f32_fp8_e32 v[202:203], v218
	v_cvt_pk_f32_fp8_sdwa v[204:205], v218 src0_sel:WORD_1
	v_cvt_pk_f32_fp8_e32 v[206:207], v219
	v_cvt_pk_f32_fp8_sdwa v[208:209], v219 src0_sel:WORD_1
	v_cvt_pk_bf16_f32 v4, v202, v203
	v_cvt_pk_bf16_f32 v5, v204, v205
	v_cvt_pk_bf16_f32 v6, v206, v207
	v_cvt_pk_bf16_f32 v7, v208, v209
	s_waitcnt vmcnt(19)
	v_cvt_pk_f32_fp8_e32 v[210:211], v220
	v_cvt_pk_f32_fp8_sdwa v[212:213], v220 src0_sel:WORD_1
	v_cvt_pk_f32_fp8_e32 v[214:215], v221
	v_cvt_pk_f32_fp8_sdwa v[216:217], v221 src0_sel:WORD_1
	v_cvt_pk_bf16_f32 v8, v210, v211
	v_cvt_pk_bf16_f32 v9, v212, v213
	v_cvt_pk_bf16_f32 v10, v214, v215
	v_cvt_pk_bf16_f32 v11, v216, v217
	s_waitcnt vmcnt(18)
	v_cvt_pk_f32_fp8_e32 v[202:203], v222
	v_cvt_pk_f32_fp8_sdwa v[204:205], v222 src0_sel:WORD_1
	v_cvt_pk_f32_fp8_e32 v[206:207], v223
	v_cvt_pk_f32_fp8_sdwa v[208:209], v223 src0_sel:WORD_1
	v_cvt_pk_bf16_f32 v12, v202, v203
	v_cvt_pk_bf16_f32 v13, v204, v205
	v_cvt_pk_bf16_f32 v14, v206, v207
	v_cvt_pk_bf16_f32 v15, v208, v209
	s_waitcnt vmcnt(17)
	v_cvt_pk_f32_fp8_e32 v[210:211], v224
	v_cvt_pk_f32_fp8_sdwa v[212:213], v224 src0_sel:WORD_1
	v_cvt_pk_f32_fp8_e32 v[214:215], v225
	v_cvt_pk_f32_fp8_sdwa v[216:217], v225 src0_sel:WORD_1
	v_cvt_pk_bf16_f32 v16, v210, v211
	v_cvt_pk_bf16_f32 v17, v212, v213
	v_cvt_pk_bf16_f32 v18, v214, v215
	v_cvt_pk_bf16_f32 v19, v216, v217
	s_waitcnt vmcnt(16)
	v_cvt_pk_f32_fp8_e32 v[202:203], v226
	v_cvt_pk_f32_fp8_sdwa v[204:205], v226 src0_sel:WORD_1
	v_cvt_pk_f32_fp8_e32 v[206:207], v227
	v_cvt_pk_f32_fp8_sdwa v[208:209], v227 src0_sel:WORD_1
	v_cvt_pk_bf16_f32 v20, v202, v203
	v_cvt_pk_bf16_f32 v21, v204, v205
	v_cvt_pk_bf16_f32 v22, v206, v207
	v_cvt_pk_bf16_f32 v23, v208, v209
	s_waitcnt vmcnt(15)
	v_cvt_pk_f32_fp8_e32 v[210:211], v228
	v_cvt_pk_f32_fp8_sdwa v[212:213], v228 src0_sel:WORD_1
	v_cvt_pk_f32_fp8_e32 v[214:215], v229
	v_cvt_pk_f32_fp8_sdwa v[216:217], v229 src0_sel:WORD_1
	v_cvt_pk_bf16_f32 v24, v210, v211
	v_cvt_pk_bf16_f32 v25, v212, v213
	v_cvt_pk_bf16_f32 v26, v214, v215
	v_cvt_pk_bf16_f32 v27, v216, v217
	s_waitcnt vmcnt(14)
	v_cvt_pk_f32_fp8_e32 v[202:203], v230
	v_cvt_pk_f32_fp8_sdwa v[204:205], v230 src0_sel:WORD_1
	v_cvt_pk_f32_fp8_e32 v[206:207], v231
	v_cvt_pk_f32_fp8_sdwa v[208:209], v231 src0_sel:WORD_1
	v_cvt_pk_bf16_f32 v28, v202, v203
	v_cvt_pk_bf16_f32 v29, v204, v205
	v_cvt_pk_bf16_f32 v30, v206, v207
	v_cvt_pk_bf16_f32 v31, v208, v209
	s_waitcnt vmcnt(13)
	v_cvt_pk_f32_fp8_e32 v[210:211], v232
	v_cvt_pk_f32_fp8_sdwa v[212:213], v232 src0_sel:WORD_1
	v_cvt_pk_f32_fp8_e32 v[214:215], v233
	v_cvt_pk_f32_fp8_sdwa v[216:217], v233 src0_sel:WORD_1
	v_cvt_pk_bf16_f32 v32, v210, v211
	v_cvt_pk_bf16_f32 v33, v212, v213
	v_cvt_pk_bf16_f32 v34, v214, v215
	v_cvt_pk_bf16_f32 v35, v216, v217
	s_and_b32 s14, s10, 0x7fc
	s_cmp_lt_u32 s14, 29
	s_waitcnt vmcnt(8)
	ds_write_b128 v170, v[44:47]
	s_waitcnt vmcnt(7)
	ds_write_b128 v170, v[48:51] offset:544
	s_waitcnt vmcnt(6)
	ds_write_b128 v170, v[60:63] offset:1088
	s_waitcnt vmcnt(5)
	ds_write_b128 v170, v[68:71] offset:1632
	s_waitcnt vmcnt(4)
	ds_write_b128 v170, v[84:87] offset:2176
	s_waitcnt vmcnt(3)
	ds_write_b128 v170, v[88:91] offset:2720
	s_waitcnt vmcnt(2)
	ds_write_b128 v170, v[100:103] offset:3264
	s_waitcnt vmcnt(1)
	ds_write_b128 v170, v[108:111] offset:3808
	s_cbranch_scc1 .LBB0_998
; #define LAS __attribute__((address_space(3)))
; #define P4_LOAD(ch) do { const u32x4 kk_ = *(const LAS u32x4*)(idxs + tok * 256 + (ch) * 32 + wrow); \
;       _Pragma("unroll") for (int i = 0; i < 8; ++i) { \
;       const int key = (int)((kk_[i >> 1] >> (16 * (i & 1))) & 0xffffu); stg[i] = *(const u32x4*)(cbase + (size_t)key * 256); } } while (0)
; #define P4_WRITE(bufp) do { _Pragma("unroll") for (int i = 0; i < 8; ++i) \
;       *(LAS u32x4*)((bufp) + (wrow + i) * CROW + 16 * (wch ^ (lane >> 5))) = stg[i]; } while (0)
; __device__ __forceinline__ void p4_attn(const Params& p, unsigned char* lds, int bid, int nb, bool dry) {
;     ...
;     P4_LOAD(0);
;     P4_WRITE(cbuf + tok * CTOK);
;     if (nch > 1) P4_LOAD(1);
;     float m_run = -1e30f, l_run = 0.f;
;     f32x4 o[16];
; #pragma unroll
;     for (int ct = 0; ct < 16; ++ct) o[ct] = (f32x4){0.f, 0.f, 0.f, 0.f};
;     epoch += 2u; pair_sync(pcnt, epoch, lane);
;     for (int ch = 0; ch < nch; ++ch) {
;       LAS unsigned char* cb = cbuf + (ch & 1) * CBUF + tok * CTOK;
;       if (ch + 1 < nch) { P4_WRITE(cbuf + ((ch + 1) & 1) * CBUF + tok * CTOK); if (ch + 2 < nch) P4_LOAD(ch + 2); }
	ds_read_b128 v[36:39], v167 offset:64
	s_waitcnt lgkmcnt(0)
	v_lshlrev_b32_e32 v0, 9, v36
	v_and_b32_e32 v0, 0x1fffe00, v0
	v_lshl_add_u64 v[2:3], v[160:161], 0, v[0:1]
	v_lshlrev_b32_sdwa v0, v171, v36 dst_sel:DWORD dst_unused:UNUSED_PAD src0_sel:DWORD src1_sel:WORD_1
	v_lshl_add_u64 v[206:207], v[160:161], 0, v[0:1]
	global_load_dwordx4 v[202:205], v[2:3], off
	global_load_dwordx4 v[206:209], v[206:207], off
	v_lshlrev_b32_e32 v0, 9, v37
	v_and_b32_e32 v0, 0x1fffe00, v0
	v_lshl_add_u64 v[2:3], v[160:161], 0, v[0:1]
	v_lshlrev_b32_sdwa v0, v171, v37 dst_sel:DWORD dst_unused:UNUSED_PAD src0_sel:DWORD src1_sel:WORD_1
	v_lshl_add_u64 v[214:215], v[160:161], 0, v[0:1]
	global_load_dwordx4 v[210:213], v[2:3], off
	global_load_dwordx4 v[214:217], v[214:215], off
	v_lshlrev_b32_e32 v0, 9, v38
	v_and_b32_e32 v0, 0x1fffe00, v0
	v_lshl_add_u64 v[2:3], v[160:161], 0, v[0:1]
	v_lshlrev_b32_sdwa v0, v171, v38 dst_sel:DWORD dst_unused:UNUSED_PAD src0_sel:DWORD src1_sel:WORD_1
	v_lshl_add_u64 v[222:223], v[160:161], 0, v[0:1]
	global_load_dwordx4 v[218:221], v[2:3], off
	global_load_dwordx4 v[222:225], v[222:223], off
	v_lshlrev_b32_e32 v0, 9, v39
	v_and_b32_e32 v0, 0x1fffe00, v0
	v_lshl_add_u64 v[2:3], v[160:161], 0, v[0:1]
	v_lshlrev_b32_sdwa v0, v171, v39 dst_sel:DWORD dst_unused:UNUSED_PAD src0_sel:DWORD src1_sel:WORD_1
	v_lshl_add_u64 v[230:231], v[160:161], 0, v[0:1]
	global_load_dwordx4 v[226:229], v[2:3], off
	global_load_dwordx4 v[230:233], v[230:231], off
	s_cmp_lt_u32 s14, 61
	s_cbranch_scc1 .LBB0_998
	ds_read_b128 v[36:39], v167 offset:128
	s_waitcnt lgkmcnt(0)
	v_lshlrev_b32_e32 v0, 9, v36
	v_and_b32_e32 v0, 0x1fffe00, v0
	v_lshl_add_u64 v[2:3], v[160:161], 0, v[0:1]
	v_lshlrev_b32_sdwa v0, v171, v36 dst_sel:DWORD dst_unused:UNUSED_PAD src0_sel:DWORD src1_sel:WORD_1
	v_lshl_add_u64 v[48:49], v[160:161], 0, v[0:1]
	global_load_dwordx4 v[44:47], v[2:3], off
	global_load_dwordx4 v[48:51], v[48:49], off
	v_lshlrev_b32_e32 v0, 9, v37
	v_and_b32_e32 v0, 0x1fffe00, v0
	v_lshl_add_u64 v[2:3], v[160:161], 0, v[0:1]
	v_lshlrev_b32_sdwa v0, v171, v37 dst_sel:DWORD dst_unused:UNUSED_PAD src0_sel:DWORD src1_sel:WORD_1
	v_lshl_add_u64 v[68:69], v[160:161], 0, v[0:1]
	global_load_dwordx4 v[60:63], v[2:3], off
	global_load_dwordx4 v[68:71], v[68:69], off
	v_lshlrev_b32_e32 v0, 9, v38
	v_and_b32_e32 v0, 0x1fffe00, v0
	v_lshl_add_u64 v[2:3], v[160:161], 0, v[0:1]
	v_lshlrev_b32_sdwa v0, v171, v38 dst_sel:DWORD dst_unused:UNUSED_PAD src0_sel:DWORD src1_sel:WORD_1
	v_lshl_add_u64 v[88:89], v[160:161], 0, v[0:1]
	global_load_dwordx4 v[84:87], v[2:3], off
	global_load_dwordx4 v[88:91], v[88:89], off
	v_lshlrev_b32_e32 v0, 9, v39
	v_and_b32_e32 v0, 0x1fffe00, v0
	v_lshl_add_u64 v[2:3], v[160:161], 0, v[0:1]
	v_lshlrev_b32_sdwa v0, v171, v39 dst_sel:DWORD dst_unused:UNUSED_PAD src0_sel:DWORD src1_sel:WORD_1
	v_lshl_add_u64 v[108:109], v[160:161], 0, v[0:1]
	global_load_dwordx4 v[100:103], v[2:3], off
	global_load_dwordx4 v[108:111], v[108:109], off

; #define LAS __attribute__((address_space(3)))
; __device__ __forceinline__ void p4_attn(const Params& p, unsigned char* lds, int bid, int nb, bool dry) {
;     ...
;     unsigned char* qrow = QL + (size_t)tg * 8192 + head * 256;
;     bf16x8 qB[8];
; #pragma unroll
;     for (int s = 0; s < 8; ++s) { const u32x2 qw = *(const u32x2*)(qrow + 32 * s + 8 * g);
;     ...
;       f32x4 s0 = (f32x4){0.f, 0.f, 0.f, 0.f}, s1 = (f32x4){0.f, 0.f, 0.f, 0.f};
; #pragma unroll
;       for (int s = 0; s < 8; ++s) {
;         const bf16x8 a0 = *(const LAS bf16x8*)(cb + r16 * CROW + s * 64 + qoff);
;         const bf16x8 a1 = *(const LAS bf16x8*)(cb + (16 + r16) * CROW + s * 64 + qoff);
;         s0 = __builtin_amdgcn_mfma_f32_16x16x32_bf16(a0, qB[s], s0, 0, 0, 0);
;         s1 = __builtin_amdgcn_mfma_f32_16x16x32_bf16(a1, qB[s], s1, 0, 0, 0);
;       }
;       const int slotb = ch * 32 + 4 * g;
;       const u32x2 k0 = *(const LAS u32x2*)(idxs + tok * 256 + slotb), k1 = *(const LAS u32x2*)(idxs + tok * 256 + slotb + 16);
.LBB0_1007:
	s_lshl_b32 s37, s36, 2
	s_add_i32 s37, s37, s0
	s_lshl_b32 s38, s37, 13
	s_mov_b32 s39, 0
	v_lshl_add_u64 v[194:195], v[152:153], 0, s[38:39]
	v_lshl_add_u64 v[194:195], v[194:195], 0, v[154:155]
	global_load_dwordx2 v[218:219], v[194:195], off
	global_load_dwordx2 v[220:221], v[194:195], off offset:32
	global_load_dwordx2 v[222:223], v[194:195], off offset:64
	global_load_dwordx2 v[224:225], v[194:195], off offset:96
	global_load_dwordx2 v[226:227], v[194:195], off offset:128
	global_load_dwordx2 v[228:229], v[194:195], off offset:160
	global_load_dwordx2 v[230:231], v[194:195], off offset:192
	global_load_dwordx2 v[232:233], v[194:195], off offset:224
	s_bitcmp1_b32 s10, 0
	s_cselect_b32 s11, 0x11000, 0
	s_add_i32 s12, s5, s11
	s_lshl_b32 s13, s10, 5
	v_add3_u32 v2, s12, v168, v162
	ds_read_b128 v[234:237], v2
	ds_read_b128 v[238:241], v2 offset:8704
	ds_read_b128 v[242:245], v2 offset:64
	ds_read_b128 v[246:249], v2 offset:8768
	ds_read_b128 v[250:253], v2 offset:128
	ds_read_b128 v[188:191], v2 offset:8832
	v_or_b32_e32 v0, s13, v148
	v_lshl_add_u32 v3, v0, 1, s3
	s_waitcnt lgkmcnt(5)
	v_mfma_f32_16x16x32_bf16 v[140:143], v[234:237], v[4:7], 0
	ds_read_b128 v[234:237], v2 offset:192
	s_waitcnt lgkmcnt(5)
	v_mfma_f32_16x16x32_bf16 v[144:147], v[238:241], v[4:7], 0
	ds_read_b128 v[238:241], v2 offset:8896
	ds_read2_b64 v[184:187], v3 offset1:4
	s_waitcnt lgkmcnt(6)
	v_mfma_f32_16x16x32_bf16 v[140:143], v[242:245], v[8:11], v[140:143]
	ds_read_b128 v[242:245], v2 offset:256
	s_waitcnt lgkmcnt(6)
	v_mfma_f32_16x16x32_bf16 v[144:147], v[246:249], v[8:11], v[144:147]
	ds_read_b128 v[246:249], v2 offset:8960
	s_waitcnt lgkmcnt(6)
	v_mfma_f32_16x16x32_bf16 v[140:143], v[250:253], v[12:15], v[140:143]
	ds_read_b128 v[250:253], v2 offset:320
	s_waitcnt lgkmcnt(6)
	v_mfma_f32_16x16x32_bf16 v[144:147], v[188:191], v[12:15], v[144:147]
	ds_read_b128 v[188:191], v2 offset:9024
	s_waitcnt lgkmcnt(6)
	v_mfma_f32_16x16x32_bf16 v[140:143], v[234:237], v[16:19], v[140:143]
	ds_read_b128 v[234:237], v2 offset:384
	s_waitcnt lgkmcnt(6)
	v_mfma_f32_16x16x32_bf16 v[144:147], v[238:241], v[16:19], v[144:147]
	ds_read_b128 v[238:241], v2 offset:9088
	s_waitcnt lgkmcnt(5)
	v_mfma_f32_16x16x32_bf16 v[140:143], v[242:245], v[20:23], v[140:143]
	ds_read_b128 v[242:245], v2 offset:448
	s_waitcnt lgkmcnt(5)
	v_mfma_f32_16x16x32_bf16 v[144:147], v[246:249], v[20:23], v[144:147]
	ds_read_b128 v[246:249], v2 offset:9152
	s_waitcnt lgkmcnt(5)
	v_mfma_f32_16x16x32_bf16 v[140:143], v[250:253], v[24:27], v[140:143]
	s_waitcnt lgkmcnt(4)
	v_mfma_f32_16x16x32_bf16 v[144:147], v[188:191], v[24:27], v[144:147]
	s_waitcnt lgkmcnt(3)
	v_mfma_f32_16x16x32_bf16 v[140:143], v[234:237], v[28:31], v[140:143]
	s_waitcnt lgkmcnt(2)
	v_mfma_f32_16x16x32_bf16 v[144:147], v[238:241], v[28:31], v[144:147]
	s_waitcnt lgkmcnt(1)
	v_mfma_f32_16x16x32_bf16 v[140:143], v[242:245], v[32:35], v[140:143]
	s_waitcnt lgkmcnt(0)
	v_mfma_f32_16x16x32_bf16 v[144:147], v[246:249], v[32:35], v[144:147]
	s_branch .Lp4_softmax

; __device__ __forceinline__ float psum16(float x) { const u32x2s r = __builtin_amdgcn_permlane16_swap(__float_as_uint(x), __float_as_uint(x), false, false); return __uint_as_float(r[0]) + __uint_as_float(r[1]); }
; __device__ __forceinline__ float psum32(float x) { const u32x2s r = __builtin_amdgcn_permlane32_swap(__float_as_uint(x), __float_as_uint(x), false, false); return __uint_as_float(r[0]) + __uint_as_float(r[1]); }
; __device__ __forceinline__ void p4_attn(const Params& p, unsigned char* lds, int bid, int nb, bool dry) {
;     ...
;     const float l = psum32(psum16(l_run));
;     const float inv = 16.f / l;
;     unsigned char* orow = qrow + 4 * g;
; #pragma unroll
;     for (int ct = 0; ct < 16; ++ct) {
;       unsigned w = __builtin_amdgcn_cvt_pk_fp8_f32(o[ct][0] * inv, o[ct][1] * inv, 0, false); w = __builtin_amdgcn_cvt_pk_fp8_f32(o[ct][2] * inv, o[ct][3] * inv, w, true);
;       if (!dry) *(unsigned*)(orow + 16 * ct) = w;
;     }
; __device__ __forceinline__ void grid_bar(unsigned* ctr, unsigned target) {
;   __syncthreads();
;   if (threadIdx.x == 0) {
;     __builtin_amdgcn_fence(__ATOMIC_RELEASE, "agent");
;     asm volatile("s_waitcnt vmcnt(0)" ::: "memory");
;     __hip_atomic_fetch_add(ctr, 1u, __ATOMIC_RELAXED, __HIP_MEMORY_SCOPE_AGENT);
;     while (__hip_atomic_load(ctr, __ATOMIC_RELAXED, __HIP_MEMORY_SCOPE_AGENT) < target) __builtin_amdgcn_s_sleep(2);
.LBB0_1019:
	v_add_f32_e32 v2, v2, v3
	v_add_f32_e32 v3, v132, v133
	v_add_f32_e32 v2, 0, v2
	v_add_f32_e32 v132, v134, v136
	v_add_f32_e32 v2, v3, v2
	v_add_f32_e32 v133, v135, v137
	v_add_f32_e32 v2, v132, v2
	v_add_f32_e32 v2, v133, v2
	v_fmac_f32_e32 v2, v174, v0
	s_cmp_eq_u32 s23, s22
	s_cbranch_scc0 .LBB0_1004
	v_mov_b32_e32 v0, v2
	s_nop 1
	v_permlane16_swap_b32_e32 v2, v0
	v_add_f32_e32 v0, v2, v0
	v_mov_b32_e32 v2, v0
	s_nop 1
	v_permlane32_swap_b32_e32 v0, v2
	v_add_f32_e32 v0, v0, v2
	v_div_scale_f32 v2, s[10:11], v0, v0, s18
	v_rcp_f32_e32 v3, v2
	v_mov_b32_e32 v7, v1
	s_add_i32 s20, s20, 1
	s_mul_i32 s10, s20, s89
	v_fma_f32 v4, -v2, v3, 1.0
	v_fmac_f32_e32 v3, v4, v3
	v_div_scale_f32 v4, vcc, s18, v0, s18
	v_mul_f32_e32 v5, v4, v3
	v_fma_f32 v6, -v2, v5, v4
	v_fmac_f32_e32 v5, v6, v3
	v_fma_f32 v2, -v2, v5, v4
	v_div_fmas_f32 v2, v2, v3, v5
	v_div_fixup_f32 v0, v2, v0, s18
	v_mul_f32_e32 v20, v128, v0
	v_mul_f32_e32 v21, v129, v0
	v_mov_b32_e32 v4, v1
	v_cvt_pk_fp8_f32 v4, v20, v21
	v_mul_f32_e32 v22, v130, v0
	v_mul_f32_e32 v23, v131, v0
	v_cvt_pk_fp8_f32 v4, v22, v23 op_sel:[0,0,1]
	v_mul_f32_e32 v20, v124, v0
	v_mul_f32_e32 v21, v125, v0
	v_mov_b32_e32 v5, v1
	v_cvt_pk_fp8_f32 v5, v20, v21
	v_mul_f32_e32 v22, v126, v0
	v_mul_f32_e32 v23, v127, v0
	v_cvt_pk_fp8_f32 v5, v22, v23 op_sel:[0,0,1]
	v_mul_f32_e32 v20, v120, v0
	v_mul_f32_e32 v21, v121, v0
	v_mov_b32_e32 v6, v1
	v_cvt_pk_fp8_f32 v6, v20, v21
	v_mul_f32_e32 v22, v122, v0
	v_mul_f32_e32 v23, v123, v0
	v_cvt_pk_fp8_f32 v6, v22, v23 op_sel:[0,0,1]
	v_mul_f32_e32 v20, v116, v0
	v_mul_f32_e32 v21, v117, v0
	v_mov_b32_e32 v7, v1
	v_cvt_pk_fp8_f32 v7, v20, v21
	v_mul_f32_e32 v22, v118, v0
	v_mul_f32_e32 v23, v119, v0
	v_cvt_pk_fp8_f32 v7, v22, v23 op_sel:[0,0,1]
	v_mul_f32_e32 v20, v112, v0
	v_mul_f32_e32 v21, v113, v0
	v_mov_b32_e32 v8, v1
	v_cvt_pk_fp8_f32 v8, v20, v21
	v_mul_f32_e32 v22, v114, v0
	v_mul_f32_e32 v23, v115, v0
	v_cvt_pk_fp8_f32 v8, v22, v23 op_sel:[0,0,1]
	v_mul_f32_e32 v20, v104, v0
	v_mul_f32_e32 v21, v105, v0
	v_mov_b32_e32 v9, v1
	v_cvt_pk_fp8_f32 v9, v20, v21
	v_mul_f32_e32 v22, v106, v0
	v_mul_f32_e32 v23, v107, v0
	v_cvt_pk_fp8_f32 v9, v22, v23 op_sel:[0,0,1]
	v_mul_f32_e32 v20, v96, v0
	v_mul_f32_e32 v21, v97, v0
	v_mov_b32_e32 v10, v1
	v_cvt_pk_fp8_f32 v10, v20, v21
	v_mul_f32_e32 v22, v98, v0
	v_mul_f32_e32 v23, v99, v0
	v_cvt_pk_fp8_f32 v10, v22, v23 op_sel:[0,0,1]
	v_mul_f32_e32 v20, v92, v0
	v_mul_f32_e32 v21, v93, v0
	v_mov_b32_e32 v11, v1
	v_cvt_pk_fp8_f32 v11, v20, v21
	v_mul_f32_e32 v22, v94, v0
	v_mul_f32_e32 v23, v95, v0
	v_cvt_pk_fp8_f32 v11, v22, v23 op_sel:[0,0,1]
	v_mul_f32_e32 v20, v80, v0
	v_mul_f32_e32 v21, v81, v0
	v_mov_b32_e32 v12, v1
	v_cvt_pk_fp8_f32 v12, v20, v21
	v_mul_f32_e32 v22, v82, v0
	v_mul_f32_e32 v23, v83, v0
	v_cvt_pk_fp8_f32 v12, v22, v23 op_sel:[0,0,1]
	v_mul_f32_e32 v20, v76, v0
	v_mul_f32_e32 v21, v77, v0
	v_mov_b32_e32 v13, v1
	v_cvt_pk_fp8_f32 v13, v20, v21
	v_mul_f32_e32 v22, v78, v0
	v_mul_f32_e32 v23, v79, v0
	v_cvt_pk_fp8_f32 v13, v22, v23 op_sel:[0,0,1]
	v_mul_f32_e32 v20, v72, v0
	v_mul_f32_e32 v21, v73, v0
	v_mov_b32_e32 v14, v1
	v_cvt_pk_fp8_f32 v14, v20, v21
	v_mul_f32_e32 v22, v74, v0
	v_mul_f32_e32 v23, v75, v0
	v_cvt_pk_fp8_f32 v14, v22, v23 op_sel:[0,0,1]
	v_mul_f32_e32 v20, v64, v0
	v_mul_f32_e32 v21, v65, v0
	v_mov_b32_e32 v15, v1
	v_cvt_pk_fp8_f32 v15, v20, v21
	v_mul_f32_e32 v22, v66, v0
	v_mul_f32_e32 v23, v67, v0
	v_cvt_pk_fp8_f32 v15, v22, v23 op_sel:[0,0,1]
	v_mul_f32_e32 v20, v56, v0
	v_mul_f32_e32 v21, v57, v0
	v_mov_b32_e32 v16, v1
	v_cvt_pk_fp8_f32 v16, v20, v21
	v_mul_f32_e32 v22, v58, v0
	v_mul_f32_e32 v23, v59, v0
	v_cvt_pk_fp8_f32 v16, v22, v23 op_sel:[0,0,1]
	v_mul_f32_e32 v20, v52, v0
	v_mul_f32_e32 v21, v53, v0
	v_mov_b32_e32 v17, v1
	v_cvt_pk_fp8_f32 v17, v20, v21
	v_mul_f32_e32 v22, v54, v0
	v_mul_f32_e32 v23, v55, v0
	v_cvt_pk_fp8_f32 v17, v22, v23 op_sel:[0,0,1]
	v_mul_f32_e32 v20, v40, v0
	v_mul_f32_e32 v21, v41, v0
	v_mov_b32_e32 v18, v1
	v_cvt_pk_fp8_f32 v18, v20, v21
	v_mul_f32_e32 v22, v42, v0
	v_mul_f32_e32 v23, v43, v0
	v_cvt_pk_fp8_f32 v18, v22, v23 op_sel:[0,0,1]
	v_mul_f32_e32 v20, v36, v0
	v_mul_f32_e32 v21, v37, v0
	v_mov_b32_e32 v19, v1
	v_cvt_pk_fp8_f32 v19, v20, v21
	v_mul_f32_e32 v22, v38, v0
	v_mul_f32_e32 v23, v39, v0
	v_cvt_pk_fp8_f32 v19, v22, v23 op_sel:[0,0,1]
	v_lshlrev_b32_e32 v24, 2, v148
	v_mov_b32_e32 v25, 0
	v_lshl_add_u64 v[24:25], v[158:159], 0, v[24:25]
	s_add_i32 s1, s1, s89
	s_cmpk_gt_i32 s10, 0x1fff
	s_nop 1
	v_permlane32_swap_b32_e32 v4, v6
	v_permlane32_swap_b32_e32 v5, v7
	v_permlane32_swap_b32_e32 v8, v10
	v_permlane32_swap_b32_e32 v9, v11
	v_permlane32_swap_b32_e32 v12, v14
	v_permlane32_swap_b32_e32 v13, v15
	v_permlane32_swap_b32_e32 v16, v18
	v_permlane32_swap_b32_e32 v17, v19
	v_permlane16_swap_b32_e32 v4, v5
	v_permlane16_swap_b32_e32 v6, v7
	v_permlane16_swap_b32_e32 v8, v9
	v_permlane16_swap_b32_e32 v10, v11
	v_permlane16_swap_b32_e32 v12, v13
	v_permlane16_swap_b32_e32 v14, v15
	v_permlane16_swap_b32_e32 v16, v17
	v_permlane16_swap_b32_e32 v18, v19
	s_nop 1
	global_store_dwordx4 v[24:25], v[4:7], off
	global_store_dwordx4 v[24:25], v[8:11], off offset:64
	global_store_dwordx4 v[24:25], v[12:15], off offset:128
	global_store_dwordx4 v[24:25], v[16:19], off offset:192
	s_cbranch_scc0 .LBB0_991
	s_barrier
	s_barrier
	s_mov_b64 s[4:5], exec
	v_readlane_b32 s0, v254, 44
	v_readlane_b32 s1, v254, 45
	s_and_b64 s[0:1], s[4:5], s[0:1]
	s_mov_b64 exec, s[0:1]
	s_cbranch_execz .LBB0_1028
	s_mov_b64 s[8:9], exec
	buffer_wbl2 sc1
	s_waitcnt vmcnt(0)
	s_waitcnt vmcnt(0)
	v_mbcnt_lo_u32_b32 v0, s8, 0
	v_mbcnt_hi_u32_b32 v0, s9, v0
	v_cmp_eq_u32_e32 vcc, 0, v0
	s_and_saveexec_b64 s[10:11], vcc
	s_cbranch_execz .LBB0_1024
	s_bcnt1_i32_b64 s0, s[8:9]
	v_mov_b32_e32 v1, s0
	v_readlane_b32 s0, v254, 20
	v_mov_b32_e32 v0, 0
	v_readlane_b32 s1, v254, 21
	s_nop 4
	global_atomic_add v0, v1, s[0:1]
